# adds B3 state-load batching and next-row prefetch in the fp4 table quantisation loops hosted in B1
# baseline (speedup 1.0000x reference)
; __device__ __forceinline__ int otid() { int t = threadIdx.x; asm volatile("" : "+v"(t)); return t; }
; __device__ void quant_rows(const float* src, unsigned char* dst, float* scales, int row_begin, int nrows) {
;   const int tid_ = otid();
;   const int lane = tid_ & 63, w = tid_ >> 6;
;   for (int row = row_begin + blockIdx.x * 4 + w; row < nrows; row += gridDim.x * 4) {
;     const f32x4* sp = (const f32x4*)(src + (size_t)row * 1024) + lane * 4;
;     f32x4 v[4];
;     float am = 0.f;
; #pragma unroll
;     for (int k = 0; k < 4; ++k) {
;       v[k] = sp[k];
;       am = fmaxf(am, fmaxf(fmaxf(fabsf(v[k].x), fabsf(v[k].y)), fmaxf(fabsf(v[k].z), fabsf(v[k].w))));
;     }
;     am = fmaxf(am, __shfl_xor(am, 1)); am = fmaxf(am, __shfl_xor(am, 2)); am = fmaxf(am, __shfl_xor(am, 4));
;     am = fmaxf(am, __shfl_xor(am, 8)); am = fmaxf(am, __shfl_xor(am, 16)); am = fmaxf(am, __shfl_xor(am, 32));
;     const float sc = am > 0.f ? 6.f / am : 1.f;
;     u32x2 o;
; #pragma unroll
;     for (int k = 0; k < 2; ++k) {
;       unsigned wd = 0u;
;       wd = __builtin_amdgcn_cvt_scalef32_pk_fp4_f32(wd, v[2 * k].x * sc, v[2 * k].y * sc, 1.0f, 0);
;       wd = __builtin_amdgcn_cvt_scalef32_pk_fp4_f32(wd, v[2 * k].z * sc, v[2 * k].w * sc, 1.0f, 1);
;       wd = __builtin_amdgcn_cvt_scalef32_pk_fp4_f32(wd, v[2 * k + 1].x * sc, v[2 * k + 1].y * sc, 1.0f, 2);
;       wd = __builtin_amdgcn_cvt_scalef32_pk_fp4_f32(wd, v[2 * k + 1].z * sc, v[2 * k + 1].w * sc, 1.0f, 3);
;       o[k] = wd;
;     }
;     ((u32x2*)(dst + (size_t)row * 512))[lane] = o;
;     if (lane == 0) scales[row] = am > 0.f ? am * (1.f / 6.f) : 1.f;
;   }
.LBB0_443:
	v_ashrrev_i32_e32 v3, 31, v2
	v_lshlrev_b64 v[30:31], 12, v[2:3]
	s_waitcnt vmcnt(14)
	v_lshl_add_u64 v[42:43], v[20:21], 0, v[30:31]
	v_add_u32_e32 v200, s86, v2
	v_cmp_gt_i32_e32 vcc, s19, v200
	s_lshl_b32 s57, s86, 12
	v_mov_b32_e32 v200, s57
	v_cndmask_b32_e32 v200, 0, v200, vcc
	v_add_co_u32_e32 v194, vcc, v200, v42
	s_nop 1
	v_addc_co_u32_e32 v195, vcc, 0, v43, vcc
	global_load_dwordx4 v[30:33], v[42:43], off
	global_load_dwordx4 v[34:37], v[42:43], off offset:16
	global_load_dwordx4 v[38:41], v[42:43], off offset:32
	s_nop 0
	global_load_dwordx4 v[42:45], v[42:43], off offset:48
	global_load_dwordx4 v[196:199], v[194:195], off
	global_load_dwordx4 v[196:199], v[194:195], off offset:16
	global_load_dwordx4 v[196:199], v[194:195], off offset:32
	global_load_dwordx4 v[196:199], v[194:195], off offset:48
	s_mov_b32 s23, 0x40c00000
	s_waitcnt vmcnt(7)
	v_max_f32_e64 v0, |v33|, |v33|
	v_max_f32_e64 v46, |v32|, |v32|
	s_waitcnt vmcnt(6)
	v_max_f32_e64 v47, |v37|, |v37|
	v_max_f32_e64 v48, |v36|, |v36|
	s_waitcnt vmcnt(5)
	v_max_f32_e64 v49, |v41|, |v41|
	v_max_f32_e64 v50, |v40|, |v40|
	s_waitcnt vmcnt(4)
	v_max_f32_e64 v51, |v45|, |v45|
	v_max_f32_e64 v52, |v44|, |v44|
	v_max_f32_e32 v0, v46, v0
	v_max_f32_e32 v46, v48, v47
	v_max_f32_e32 v47, v50, v49
	v_max_f32_e32 v48, v52, v51
	v_max3_f32 v0, |v30|, |v31|, v0
	v_max3_f32 v46, |v34|, |v35|, v46
	v_max3_f32 v47, |v38|, |v39|, v47
	v_max3_f32 v48, |v42|, |v43|, v48
	v_max3_f32 v0, v0, 0, v46
	v_max3_f32 v0, v0, v47, v48
	ds_bpermute_b32 v46, v24, v0
	v_mov_b32_e32 v47, v1
	s_waitcnt lgkmcnt(0)
	v_max_f32_e32 v46, v46, v46
	v_max_f32_e32 v0, v0, v46
	ds_bpermute_b32 v46, v25, v0
	s_waitcnt lgkmcnt(0)
	v_max_f32_e32 v46, v46, v46
	v_max_f32_e32 v0, v0, v46
	ds_bpermute_b32 v46, v26, v0
	s_waitcnt lgkmcnt(0)
	v_max_f32_e32 v46, v46, v46
	v_max_f32_e32 v0, v0, v46
	ds_bpermute_b32 v46, v27, v0
	s_waitcnt lgkmcnt(0)
	v_max_f32_e32 v46, v46, v46
	v_max_f32_e32 v0, v0, v46
	ds_bpermute_b32 v46, v28, v0
	s_waitcnt lgkmcnt(0)
	v_max_f32_e32 v46, v46, v46
	v_max_f32_e32 v0, v0, v46
	ds_bpermute_b32 v48, v29, v0
	v_mov_b32_e32 v46, v1
	s_waitcnt lgkmcnt(0)
	v_max_f32_e32 v48, v48, v48
	v_max_f32_e32 v0, v0, v48
	v_div_scale_f32 v50, s[20:21], v0, v0, s23
	v_rcp_f32_e32 v51, v50
	v_div_scale_f32 v52, vcc, s23, v0, s23
	v_lshlrev_b64 v[48:49], 9, v[2:3]
	v_fma_f32 v53, -v50, v51, 1.0
	v_fmac_f32_e32 v51, v53, v51
	v_mul_f32_e32 v53, v52, v51
	v_fma_f32 v54, -v50, v53, v52
	v_fmac_f32_e32 v53, v54, v51
	v_fma_f32 v50, -v50, v53, v52
	v_div_fmas_f32 v50, v50, v51, v53
	v_div_fixup_f32 v50, v50, v0, s23
	v_cmp_lt_f32_e32 vcc, 0, v0
	s_nop 1
	v_cndmask_b32_e32 v50, 1.0, v50, vcc
	v_mul_f32_e32 v30, v30, v50
	v_mul_f32_e32 v31, v31, v50
	v_mul_f32_e32 v38, v38, v50
	v_mul_f32_e32 v39, v39, v50
	v_mul_f32_e32 v32, v32, v50
	v_mul_f32_e32 v33, v33, v50
	v_mul_f32_e32 v40, v40, v50
	v_mul_f32_e32 v41, v41, v50
	v_cvt_scalef32_pk_fp4_f32 v46, v30, v31, 1.0
	v_cvt_scalef32_pk_fp4_f32 v47, v38, v39, 1.0
	v_mul_f32_e32 v34, v34, v50
	v_mul_f32_e32 v35, v35, v50
	v_mul_f32_e32 v42, v42, v50
	v_mul_f32_e32 v43, v43, v50
	v_cvt_scalef32_pk_fp4_f32 v46, v32, v33, 1.0 op_sel:[0,0,1,0]
	v_cvt_scalef32_pk_fp4_f32 v47, v40, v41, 1.0 op_sel:[0,0,1,0]
	v_mul_f32_e32 v36, v36, v50
	v_mul_f32_e32 v37, v37, v50
	v_mul_f32_e32 v44, v44, v50
	v_mul_f32_e32 v45, v45, v50
	v_cvt_scalef32_pk_fp4_f32 v46, v34, v35, 1.0 op_sel:[0,0,0,1]
	v_cvt_scalef32_pk_fp4_f32 v47, v42, v43, 1.0 op_sel:[0,0,0,1]
	v_cvt_scalef32_pk_fp4_f32 v46, v36, v37, 1.0 op_sel:[0,0,1,1]
	v_cvt_scalef32_pk_fp4_f32 v47, v44, v45, 1.0 op_sel:[0,0,1,1]
	v_lshl_add_u64 v[30:31], v[22:23], 0, v[48:49]
	global_store_dwordx2 v[30:31], v[46:47], off
	s_and_saveexec_b64 s[20:21], s[0:1]
	s_cbranch_execz .LBB0_442
	v_mul_f32_e32 v0, 0x3e2aaaab, v0
	v_cndmask_b32_e32 v0, 1.0, v0, vcc
	v_lshl_add_u64 v[30:31], v[2:3], 2, s[8:9]
	global_store_dword v[30:31], v0, off
	s_branch .LBB0_442

; __device__ __forceinline__ int otid() { int t = threadIdx.x; asm volatile("" : "+v"(t)); return t; }
; __device__ void quant_rows(const float* src, unsigned char* dst, float* scales, int row_begin, int nrows) {
;   const int tid_ = otid();
;   const int lane = tid_ & 63, w = tid_ >> 6;
;   for (int row = row_begin + blockIdx.x * 4 + w; row < nrows; row += gridDim.x * 4) {
;     const f32x4* sp = (const f32x4*)(src + (size_t)row * 1024) + lane * 4;
;     f32x4 v[4];
;     float am = 0.f;
; #pragma unroll
;     for (int k = 0; k < 4; ++k) {
;       v[k] = sp[k];
;       am = fmaxf(am, fmaxf(fmaxf(fabsf(v[k].x), fabsf(v[k].y)), fmaxf(fabsf(v[k].z), fabsf(v[k].w))));
;     }
;     am = fmaxf(am, __shfl_xor(am, 1)); am = fmaxf(am, __shfl_xor(am, 2)); am = fmaxf(am, __shfl_xor(am, 4));
;     am = fmaxf(am, __shfl_xor(am, 8)); am = fmaxf(am, __shfl_xor(am, 16)); am = fmaxf(am, __shfl_xor(am, 32));
;     const float sc = am > 0.f ? 6.f / am : 1.f;
;     u32x2 o;
; #pragma unroll
;     for (int k = 0; k < 2; ++k) {
;       unsigned wd = 0u;
;       wd = __builtin_amdgcn_cvt_scalef32_pk_fp4_f32(wd, v[2 * k].x * sc, v[2 * k].y * sc, 1.0f, 0);
;       wd = __builtin_amdgcn_cvt_scalef32_pk_fp4_f32(wd, v[2 * k].z * sc, v[2 * k].w * sc, 1.0f, 1);
;       wd = __builtin_amdgcn_cvt_scalef32_pk_fp4_f32(wd, v[2 * k + 1].x * sc, v[2 * k + 1].y * sc, 1.0f, 2);
;       wd = __builtin_amdgcn_cvt_scalef32_pk_fp4_f32(wd, v[2 * k + 1].z * sc, v[2 * k + 1].w * sc, 1.0f, 3);
;       o[k] = wd;
;     }
;     ((u32x2*)(dst + (size_t)row * 512))[lane] = o;
;     if (lane == 0) scales[row] = am > 0.f ? am * (1.f / 6.f) : 1.f;
;   }
.LBB0_448:
	v_ashrrev_i32_e32 v3, 31, v2
	v_lshlrev_b64 v[30:31], 12, v[2:3]
	s_waitcnt vmcnt(14)
	v_lshl_add_u64 v[42:43], v[20:21], 0, v[30:31]
	v_add_u32_e32 v200, s86, v2
	v_cmp_gt_i32_e32 vcc, s19, v200
	s_lshl_b32 s57, s86, 12
	v_mov_b32_e32 v200, s57
	v_cndmask_b32_e32 v200, 0, v200, vcc
	v_add_co_u32_e32 v194, vcc, v200, v42
	s_nop 1
	v_addc_co_u32_e32 v195, vcc, 0, v43, vcc
	global_load_dwordx4 v[30:33], v[42:43], off
	global_load_dwordx4 v[34:37], v[42:43], off offset:16
	global_load_dwordx4 v[38:41], v[42:43], off offset:32
	s_nop 0
	global_load_dwordx4 v[42:45], v[42:43], off offset:48
	global_load_dwordx4 v[196:199], v[194:195], off
	global_load_dwordx4 v[196:199], v[194:195], off offset:16
	global_load_dwordx4 v[196:199], v[194:195], off offset:32
	global_load_dwordx4 v[196:199], v[194:195], off offset:48
	s_mov_b32 s22, 0x40c00000
	s_waitcnt vmcnt(7)
	v_max_f32_e64 v0, |v33|, |v33|
	v_max_f32_e64 v46, |v32|, |v32|
	s_waitcnt vmcnt(6)
	v_max_f32_e64 v47, |v37|, |v37|
	v_max_f32_e64 v48, |v36|, |v36|
	s_waitcnt vmcnt(5)
	v_max_f32_e64 v49, |v41|, |v41|
	v_max_f32_e64 v50, |v40|, |v40|
	s_waitcnt vmcnt(4)
	v_max_f32_e64 v51, |v45|, |v45|
	v_max_f32_e64 v52, |v44|, |v44|
	v_max_f32_e32 v0, v46, v0
	v_max_f32_e32 v46, v48, v47
	v_max_f32_e32 v47, v50, v49
	v_max_f32_e32 v48, v52, v51
	v_max3_f32 v0, |v30|, |v31|, v0
	v_max3_f32 v46, |v34|, |v35|, v46
	v_max3_f32 v47, |v38|, |v39|, v47
	v_max3_f32 v48, |v42|, |v43|, v48
	v_max3_f32 v0, v0, 0, v46
	v_max3_f32 v0, v0, v47, v48
	ds_bpermute_b32 v46, v24, v0
	v_mov_b32_e32 v47, v1
	s_waitcnt lgkmcnt(0)
	v_max_f32_e32 v46, v46, v46
	v_max_f32_e32 v0, v0, v46
	ds_bpermute_b32 v46, v25, v0
	s_waitcnt lgkmcnt(0)
	v_max_f32_e32 v46, v46, v46
	v_max_f32_e32 v0, v0, v46
	ds_bpermute_b32 v46, v26, v0
	s_waitcnt lgkmcnt(0)
	v_max_f32_e32 v46, v46, v46
	v_max_f32_e32 v0, v0, v46
	ds_bpermute_b32 v46, v27, v0
	s_waitcnt lgkmcnt(0)
	v_max_f32_e32 v46, v46, v46
	v_max_f32_e32 v0, v0, v46
	ds_bpermute_b32 v46, v28, v0
	s_waitcnt lgkmcnt(0)
	v_max_f32_e32 v46, v46, v46
	v_max_f32_e32 v0, v0, v46
	ds_bpermute_b32 v48, v29, v0
	v_mov_b32_e32 v46, v1
	s_waitcnt lgkmcnt(0)
	v_max_f32_e32 v48, v48, v48
	v_max_f32_e32 v0, v0, v48
	v_div_scale_f32 v50, s[20:21], v0, v0, s22
	v_rcp_f32_e32 v51, v50
	v_div_scale_f32 v52, vcc, s22, v0, s22
	v_lshlrev_b64 v[48:49], 9, v[2:3]
	v_fma_f32 v53, -v50, v51, 1.0
	v_fmac_f32_e32 v51, v53, v51
	v_mul_f32_e32 v53, v52, v51
	v_fma_f32 v54, -v50, v53, v52
	v_fmac_f32_e32 v53, v54, v51
	v_fma_f32 v50, -v50, v53, v52
	v_div_fmas_f32 v50, v50, v51, v53
	v_div_fixup_f32 v50, v50, v0, s22
	v_cmp_lt_f32_e32 vcc, 0, v0
	s_nop 1
	v_cndmask_b32_e32 v50, 1.0, v50, vcc
	v_mul_f32_e32 v30, v30, v50
	v_mul_f32_e32 v31, v31, v50
	v_mul_f32_e32 v38, v38, v50
	v_mul_f32_e32 v39, v39, v50
	v_mul_f32_e32 v32, v32, v50
	v_mul_f32_e32 v33, v33, v50
	v_mul_f32_e32 v40, v40, v50
	v_mul_f32_e32 v41, v41, v50
	v_cvt_scalef32_pk_fp4_f32 v46, v30, v31, 1.0
	v_cvt_scalef32_pk_fp4_f32 v47, v38, v39, 1.0
	v_mul_f32_e32 v34, v34, v50
	v_mul_f32_e32 v35, v35, v50
	v_mul_f32_e32 v42, v42, v50
	v_mul_f32_e32 v43, v43, v50
	v_cvt_scalef32_pk_fp4_f32 v46, v32, v33, 1.0 op_sel:[0,0,1,0]
	v_cvt_scalef32_pk_fp4_f32 v47, v40, v41, 1.0 op_sel:[0,0,1,0]
	v_mul_f32_e32 v36, v36, v50
	v_mul_f32_e32 v37, v37, v50
	v_mul_f32_e32 v44, v44, v50
	v_mul_f32_e32 v45, v45, v50
	v_cvt_scalef32_pk_fp4_f32 v46, v34, v35, 1.0 op_sel:[0,0,0,1]
	v_cvt_scalef32_pk_fp4_f32 v47, v42, v43, 1.0 op_sel:[0,0,0,1]
	v_cvt_scalef32_pk_fp4_f32 v46, v36, v37, 1.0 op_sel:[0,0,1,1]
	v_cvt_scalef32_pk_fp4_f32 v47, v44, v45, 1.0 op_sel:[0,0,1,1]
	v_lshl_add_u64 v[30:31], v[22:23], 0, v[48:49]
	global_store_dwordx2 v[30:31], v[46:47], off
	s_and_saveexec_b64 s[20:21], s[0:1]
	s_cbranch_execz .LBB0_447
	v_mul_f32_e32 v0, 0x3e2aaaab, v0
	v_cndmask_b32_e32 v0, 1.0, v0, vcc
	v_lshl_add_u64 v[30:31], v[2:3], 2, s[8:9]
	global_store_dword v[30:31], v0, off
	s_branch .LBB0_447

; __device__ __forceinline__ int otid() { int t = threadIdx.x; asm volatile("" : "+v"(t)); return t; }
; __device__ void quant_rows(const float* src, unsigned char* dst, float* scales, int row_begin, int nrows) {
;   const int tid_ = otid();
;   const int lane = tid_ & 63, w = tid_ >> 6;
;   for (int row = row_begin + blockIdx.x * 4 + w; row < nrows; row += gridDim.x * 4) {
;     const f32x4* sp = (const f32x4*)(src + (size_t)row * 1024) + lane * 4;
;     f32x4 v[4];
;     float am = 0.f;
; #pragma unroll
;     for (int k = 0; k < 4; ++k) {
;       v[k] = sp[k];
;       am = fmaxf(am, fmaxf(fmaxf(fabsf(v[k].x), fabsf(v[k].y)), fmaxf(fabsf(v[k].z), fabsf(v[k].w))));
;     }
;     am = fmaxf(am, __shfl_xor(am, 1)); am = fmaxf(am, __shfl_xor(am, 2)); am = fmaxf(am, __shfl_xor(am, 4));
;     am = fmaxf(am, __shfl_xor(am, 8)); am = fmaxf(am, __shfl_xor(am, 16)); am = fmaxf(am, __shfl_xor(am, 32));
;     const float sc = am > 0.f ? 6.f / am : 1.f;
;     u32x2 o;
; #pragma unroll
;     for (int k = 0; k < 2; ++k) {
;       unsigned wd = 0u;
;       wd = __builtin_amdgcn_cvt_scalef32_pk_fp4_f32(wd, v[2 * k].x * sc, v[2 * k].y * sc, 1.0f, 0);
;       wd = __builtin_amdgcn_cvt_scalef32_pk_fp4_f32(wd, v[2 * k].z * sc, v[2 * k].w * sc, 1.0f, 1);
;       wd = __builtin_amdgcn_cvt_scalef32_pk_fp4_f32(wd, v[2 * k + 1].x * sc, v[2 * k + 1].y * sc, 1.0f, 2);
;       wd = __builtin_amdgcn_cvt_scalef32_pk_fp4_f32(wd, v[2 * k + 1].z * sc, v[2 * k + 1].w * sc, 1.0f, 3);
;       o[k] = wd;
;     }
;     ((u32x2*)(dst + (size_t)row * 512))[lane] = o;
;     if (lane == 0) scales[row] = am > 0.f ? am * (1.f / 6.f) : 1.f;
;   }
.LBB0_641:
	v_ashrrev_i32_e32 v3, 31, v2
	v_lshlrev_b64 v[30:31], 12, v[2:3]
	s_waitcnt vmcnt(14)
	v_lshl_add_u64 v[42:43], v[20:21], 0, v[30:31]
	v_add_u32_e32 v200, s86, v2
	v_cmp_gt_i32_e32 vcc, s19, v200
	s_lshl_b32 s57, s86, 12
	v_mov_b32_e32 v200, s57
	v_cndmask_b32_e32 v200, 0, v200, vcc
	v_add_co_u32_e32 v194, vcc, v200, v42
	s_nop 1
	v_addc_co_u32_e32 v195, vcc, 0, v43, vcc
	global_load_dwordx4 v[30:33], v[42:43], off
	global_load_dwordx4 v[34:37], v[42:43], off offset:16
	global_load_dwordx4 v[38:41], v[42:43], off offset:32
	s_nop 0
	global_load_dwordx4 v[42:45], v[42:43], off offset:48
	global_load_dwordx4 v[196:199], v[194:195], off
	global_load_dwordx4 v[196:199], v[194:195], off offset:16
	global_load_dwordx4 v[196:199], v[194:195], off offset:32
	global_load_dwordx4 v[196:199], v[194:195], off offset:48
	s_mov_b32 s24, 0x40c00000
	s_waitcnt vmcnt(7)
	v_max_f32_e64 v0, |v33|, |v33|
	v_max_f32_e64 v46, |v32|, |v32|
	s_waitcnt vmcnt(6)
	v_max_f32_e64 v47, |v37|, |v37|
	v_max_f32_e64 v48, |v36|, |v36|
	s_waitcnt vmcnt(5)
	v_max_f32_e64 v49, |v41|, |v41|
	v_max_f32_e64 v50, |v40|, |v40|
	s_waitcnt vmcnt(4)
	v_max_f32_e64 v51, |v45|, |v45|
	v_max_f32_e64 v52, |v44|, |v44|
	v_max_f32_e32 v0, v46, v0
	v_max_f32_e32 v46, v48, v47
	v_max_f32_e32 v47, v50, v49
	v_max_f32_e32 v48, v52, v51
	v_max3_f32 v0, |v30|, |v31|, v0
	v_max3_f32 v46, |v34|, |v35|, v46
	v_max3_f32 v47, |v38|, |v39|, v47
	v_max3_f32 v48, |v42|, |v43|, v48
	v_max3_f32 v0, v0, 0, v46
	v_max3_f32 v0, v0, v47, v48
	ds_bpermute_b32 v46, v24, v0
	v_mov_b32_e32 v47, v1
	s_waitcnt lgkmcnt(0)
	v_max_f32_e32 v46, v46, v46
	v_max_f32_e32 v0, v0, v46
	ds_bpermute_b32 v46, v25, v0
	s_waitcnt lgkmcnt(0)
	v_max_f32_e32 v46, v46, v46
	v_max_f32_e32 v0, v0, v46
	ds_bpermute_b32 v46, v26, v0
	s_waitcnt lgkmcnt(0)
	v_max_f32_e32 v46, v46, v46
	v_max_f32_e32 v0, v0, v46
	ds_bpermute_b32 v46, v27, v0
	s_waitcnt lgkmcnt(0)
	v_max_f32_e32 v46, v46, v46
	v_max_f32_e32 v0, v0, v46
	ds_bpermute_b32 v46, v28, v0
	s_waitcnt lgkmcnt(0)
	v_max_f32_e32 v46, v46, v46
	v_max_f32_e32 v0, v0, v46
	ds_bpermute_b32 v48, v29, v0
	v_mov_b32_e32 v46, v1
	s_waitcnt lgkmcnt(0)
	v_max_f32_e32 v48, v48, v48
	v_max_f32_e32 v0, v0, v48
	v_div_scale_f32 v50, s[22:23], v0, v0, s24
	v_rcp_f32_e32 v51, v50
	v_div_scale_f32 v52, vcc, s24, v0, s24
	v_lshlrev_b64 v[48:49], 9, v[2:3]
	v_fma_f32 v53, -v50, v51, 1.0
	v_fmac_f32_e32 v51, v53, v51
	v_mul_f32_e32 v53, v52, v51
	v_fma_f32 v54, -v50, v53, v52
	v_fmac_f32_e32 v53, v54, v51
	v_fma_f32 v50, -v50, v53, v52
	v_div_fmas_f32 v50, v50, v51, v53
	v_div_fixup_f32 v50, v50, v0, s24
	v_cmp_lt_f32_e32 vcc, 0, v0
	s_nop 1
	v_cndmask_b32_e32 v50, 1.0, v50, vcc
	v_mul_f32_e32 v30, v30, v50
	v_mul_f32_e32 v31, v31, v50
	v_mul_f32_e32 v38, v38, v50
	v_mul_f32_e32 v39, v39, v50
	v_mul_f32_e32 v32, v32, v50
	v_mul_f32_e32 v33, v33, v50
	v_mul_f32_e32 v40, v40, v50
	v_mul_f32_e32 v41, v41, v50
	v_cvt_scalef32_pk_fp4_f32 v46, v30, v31, 1.0
	v_cvt_scalef32_pk_fp4_f32 v47, v38, v39, 1.0
	v_mul_f32_e32 v34, v34, v50
	v_mul_f32_e32 v35, v35, v50
	v_mul_f32_e32 v42, v42, v50
	v_mul_f32_e32 v43, v43, v50
	v_cvt_scalef32_pk_fp4_f32 v46, v32, v33, 1.0 op_sel:[0,0,1,0]
	v_cvt_scalef32_pk_fp4_f32 v47, v40, v41, 1.0 op_sel:[0,0,1,0]
	v_mul_f32_e32 v36, v36, v50
	v_mul_f32_e32 v37, v37, v50
	v_mul_f32_e32 v44, v44, v50
	v_mul_f32_e32 v45, v45, v50
	v_cvt_scalef32_pk_fp4_f32 v46, v34, v35, 1.0 op_sel:[0,0,0,1]
	v_cvt_scalef32_pk_fp4_f32 v47, v42, v43, 1.0 op_sel:[0,0,0,1]
	v_cvt_scalef32_pk_fp4_f32 v46, v36, v37, 1.0 op_sel:[0,0,1,1]
	v_cvt_scalef32_pk_fp4_f32 v47, v44, v45, 1.0 op_sel:[0,0,1,1]
	v_lshl_add_u64 v[30:31], v[22:23], 0, v[48:49]
	global_store_dwordx2 v[30:31], v[46:47], off
	s_and_saveexec_b64 s[22:23], s[0:1]
	s_cbranch_execz .LBB0_640
	v_mul_f32_e32 v0, 0x3e2aaaab, v0
	v_cndmask_b32_e32 v0, 1.0, v0, vcc
	v_lshl_add_u64 v[30:31], v[2:3], 2, s[8:9]
	global_store_dword v[30:31], v0, off
	s_branch .LBB0_640

; __device__ __forceinline__ int otid() { int t = threadIdx.x; asm volatile("" : "+v"(t)); return t; }
; __device__ void ret_out_item(const P& p, int bh, int c) {
;     ...
;   const bf16_t* Q = R + R_RQ + ((size_t)bh * 4096 + c * 128) * 128;
;   const bf16_t* Kp = R + R_RK + ((size_t)bh * 4096 + c * 128) * 128;
;   const bf16_t* VT = R + R_RVT + (size_t)bh * 128 * 4096 + c * 128;
;   const bf16_t* ST = (const bf16_t*)(ws + OFF_ST) + (size_t)(bh * 32 + c) * 16384;
;   const int tid_ = otid(); const int lane = tid_ & 63, w = tid_ >> 6, li = lane & 15, g = lane >> 4;
;   const float lg = LOG2G[hd];
;   bf16x8 qf[2][4];
; #pragma unroll
;   for (int ns = 0; ns < 2; ++ns)
; #pragma unroll
;     for (int kk = 0; kk < 4; ++kk) qf[ns][kk] = *(const bf16x8*)(Q + (size_t)(32 * w + 16 * ns + li) * 128 + (kk * 4 + g) * 8);
;   f32x4 acc[8][2];
; #pragma unroll
;   for (int es = 0; es < 8; ++es)
; #pragma unroll
;     for (int ns = 0; ns < 2; ++ns) acc[es][ns] = (f32x4){0.f, 0.f, 0.f, 0.f};
;   if (c > 0) {
; #pragma unroll
;     for (int es = 0; es < 8; ++es)
; #pragma unroll
;       for (int kk = 0; kk < 4; ++kk) {
;         const bf16x8 sf = *(const bf16x8*)(ST + (size_t)(es * 16 + li) * 128 + (kk * 4 + g) * 8);
; #pragma unroll
;         for (int ns = 0; ns < 2; ++ns) acc[es][ns] = __builtin_amdgcn_mfma_f32_16x16x32_bf16(sf, qf[ns][kk], acc[es][ns], 0, 0, 0);
;       }
.LBB0_761:
	s_ashr_i32 s10, s6, 5
	s_and_b32 s23, s6, 31
	s_mov_b64 s[0:1], 0
	s_add_u32 s8, s68, s0
	s_addc_u32 s9, s69, s1
	s_ashr_i32 s11, s10, 31
	s_lshl_b64 s[20:21], s[10:11], 20
	s_lshl_b32 s7, s23, 15
	v_mov_b32_e32 v144, v208
	s_and_b32 s22, s10, 3
	s_or_b32 s7, s20, s7
	s_add_u32 s7, s8, s7
	v_ashrrev_i32_e32 v145, 6, v144
	v_and_b32_e32 v143, 15, v144
	v_lshlrev_b32_e32 v136, 5, v145
	s_addc_u32 s11, s9, s21
	v_or_b32_e32 v138, v136, v143
	s_add_u32 s10, s7, 0x1ca84000
	v_ashrrev_i32_e32 v139, 31, v138
	s_addc_u32 s11, s11, 0
	v_bfe_u32 v142, v144, 4, 2
	v_lshlrev_b64 v[2:3], 8, v[138:139]
	v_lshl_add_u64 v[2:3], s[10:11], 0, v[2:3]
	v_lshlrev_b32_e32 v0, 4, v142
	v_or_b32_e32 v140, 16, v138
	v_lshl_add_u64 v[2:3], v[2:3], 0, v[0:1]
	v_ashrrev_i32_e32 v141, 31, v140
	global_load_dwordx4 v[84:87], v[2:3], off
	global_load_dwordx4 v[88:91], v[2:3], off offset:64
	global_load_dwordx4 v[92:95], v[2:3], off offset:128
	global_load_dwordx4 v[96:99], v[2:3], off offset:192
	v_lshlrev_b64 v[2:3], 8, v[140:141]
	v_lshl_add_u64 v[2:3], s[10:11], 0, v[2:3]
	v_lshl_add_u64 v[2:3], v[2:3], 0, v[0:1]
	global_load_dwordx4 v[100:103], v[2:3], off
	global_load_dwordx4 v[104:107], v[2:3], off offset:64
	global_load_dwordx4 v[108:111], v[2:3], off offset:128
	global_load_dwordx4 v[112:115], v[2:3], off offset:192
	s_lshl_b32 s7, s22, 2
	s_getpc_b64 s[10:11]
	s_add_u32 s10, s10, LOG2G@rel32@lo+4
	s_addc_u32 s11, s11, LOG2G@rel32@hi+12
	s_load_dword s24, s[10:11], s7 offset:0x0
	s_cmp_eq_u32 s23, 0
	v_lshlrev_b32_e32 v137, 3, v142
	s_cbranch_scc1 .LBB0_763
	s_ashr_i32 s7, s6, 31
	s_lshl_b64 s[10:11], s[6:7], 15
	s_add_u32 s10, s8, s10
	s_addc_u32 s11, s9, s11
	v_lshlrev_b32_e32 v0, 8, v143
	v_lshlrev_b32_e32 v2, 1, v137
	v_lshl_add_u64 v[52:53], s[10:11], 0, v[0:1]
	v_mov_b32_e32 v3, v1
	v_lshl_add_u64 v[20:21], v[52:53], 0, v[2:3]
	s_mov_b64 s[10:11], 0x2ba84000
	s_mov_b32 s7, 0x2ba84000
	s_waitcnt vmcnt(24)
	v_lshl_add_u64 v[32:33], v[20:21], 0, s[10:11]
	v_add_co_u32_e32 v20, vcc, s7, v20
	v_mov_b64_e32 v[252:253], v[32:33]
	s_mov_b64 s[98:99], 0x0
	v_lshl_add_u64 v[160:161], v[252:253], 0, s[98:99]
	global_load_dwordx4 v[148:151], v[160:161], off
	global_load_dwordx4 v[152:155], v[160:161], off offset:64
	global_load_dwordx4 v[156:159], v[160:161], off offset:128
	global_load_dwordx4 v[160:163], v[160:161], off offset:192
	s_mov_b64 s[98:99], 0x1000
	v_lshl_add_u64 v[176:177], v[252:253], 0, s[98:99]
	global_load_dwordx4 v[164:167], v[176:177], off
	global_load_dwordx4 v[168:171], v[176:177], off offset:64
	global_load_dwordx4 v[172:175], v[176:177], off offset:128
	global_load_dwordx4 v[176:179], v[176:177], off offset:192
	s_mov_b64 s[98:99], 0x2000
	v_lshl_add_u64 v[192:193], v[252:253], 0, s[98:99]
	global_load_dwordx4 v[180:183], v[192:193], off
	global_load_dwordx4 v[184:187], v[192:193], off offset:64
	global_load_dwordx4 v[188:191], v[192:193], off offset:128
	global_load_dwordx4 v[192:195], v[192:193], off offset:192
	s_mov_b64 s[98:99], 0x3000
	v_lshl_add_u64 v[220:221], v[252:253], 0, s[98:99]
	global_load_dwordx4 v[196:199], v[220:221], off
	global_load_dwordx4 v[200:203], v[220:221], off offset:64
	global_load_dwordx4 v[204:207], v[220:221], off offset:128
	global_load_dwordx4 v[220:223], v[220:221], off offset:192
	s_nop 0
	v_addc_co_u32_e32 v21, vcc, 0, v21, vcc
	s_mov_b64 s[10:11], 0x2ba85000
	s_waitcnt vmcnt(24)
	v_lshl_add_u64 v[40:41], v[52:53], 0, s[10:11]
	s_mov_b64 s[10:11], 0x2ba86000
	s_waitcnt vmcnt(22)
	v_lshl_add_u64 v[48:49], v[52:53], 0, s[10:11]
	s_mov_b64 s[10:11], 0x2ba87000
	v_or_b32_e32 v0, 64, v2
	v_lshl_add_u64 v[62:63], v[52:53], 0, s[10:11]
	s_waitcnt vmcnt(21)
	v_lshl_add_u64 v[58:59], v[62:63], 0, v[0:1]
	v_lshl_add_u64 v[36:37], v[40:41], 0, v[0:1]
	v_or_b32_e32 v56, 0x80, v2
	v_mov_b32_e32 v57, v1
	v_or_b32_e32 v54, 0xc0, v2
	v_mov_b32_e32 v55, v1
	v_lshl_add_u64 v[44:45], v[48:49], 0, v[0:1]
	s_mov_b64 s[10:11], 0x2ba88000
	s_waitcnt vmcnt(20)
	v_lshl_add_u64 v[66:67], v[52:53], 0, s[10:11]
	s_mov_b64 s[10:11], 0x2ba89000
	v_lshl_add_u64 v[70:71], v[52:53], 0, s[10:11]
	s_mov_b64 s[10:11], 0x2ba8a000
	s_waitcnt vmcnt(0)
	s_waitcnt vmcnt(8)
	v_mfma_f32_16x16x32_bf16 v[24:27], v[148:151], v[84:87], 0
	s_nop 0
	v_mfma_f32_16x16x32_bf16 v[20:23], v[148:151], v[100:103], 0
	v_mfma_f32_16x16x32_bf16 v[24:27], v[152:155], v[88:91], v[24:27]
	v_mfma_f32_16x16x32_bf16 v[20:23], v[152:155], v[104:107], v[20:23]
	s_nop 0
	v_mfma_f32_16x16x32_bf16 v[24:27], v[156:159], v[92:95], v[24:27]
	v_mfma_f32_16x16x32_bf16 v[20:23], v[156:159], v[108:111], v[20:23]
	v_mfma_f32_16x16x32_bf16 v[28:31], v[160:163], v[96:99], v[24:27]
	s_nop 4
	v_lshl_add_u64 v[24:25], v[40:41], 0, v[2:3]
	v_mfma_f32_16x16x32_bf16 v[20:23], v[160:163], v[112:115], v[20:23]
	v_mfma_f32_16x16x32_bf16 v[32:35], v[164:167], v[84:87], 0
	v_mfma_f32_16x16x32_bf16 v[24:27], v[164:167], v[100:103], 0
	v_mfma_f32_16x16x32_bf16 v[32:35], v[168:171], v[88:91], v[32:35]
	v_mfma_f32_16x16x32_bf16 v[24:27], v[168:171], v[104:107], v[24:27]
	v_lshl_add_u64 v[36:37], v[40:41], 0, v[56:57]
	v_mfma_f32_16x16x32_bf16 v[32:35], v[172:175], v[92:95], v[32:35]
	v_mfma_f32_16x16x32_bf16 v[24:27], v[172:175], v[108:111], v[24:27]
	v_lshl_add_u64 v[36:37], v[40:41], 0, v[54:55]
	v_mfma_f32_16x16x32_bf16 v[36:39], v[176:179], v[96:99], v[32:35]
	s_nop 2
	v_lshl_add_u64 v[32:33], v[48:49], 0, v[2:3]
	v_mfma_f32_16x16x32_bf16 v[24:27], v[176:179], v[112:115], v[24:27]
	s_mov_b64 s[98:99], 0x4000
	v_lshl_add_u64 v[160:161], v[252:253], 0, s[98:99]
	global_load_dwordx4 v[148:151], v[160:161], off
	global_load_dwordx4 v[152:155], v[160:161], off offset:64
	global_load_dwordx4 v[156:159], v[160:161], off offset:128
	global_load_dwordx4 v[160:163], v[160:161], off offset:192
	s_mov_b64 s[98:99], 0x5000
	v_lshl_add_u64 v[176:177], v[252:253], 0, s[98:99]
	global_load_dwordx4 v[164:167], v[176:177], off
	global_load_dwordx4 v[168:171], v[176:177], off offset:64
	global_load_dwordx4 v[172:175], v[176:177], off offset:128
	global_load_dwordx4 v[176:179], v[176:177], off offset:192
	s_waitcnt vmcnt(8)
; __device__ void ret_out_item(const P& p, int bh, int c) {
;     ...
;   if (c > 0) {
; #pragma unroll
;     for (int es = 0; es < 8; ++es)
; #pragma unroll
;       for (int kk = 0; kk < 4; ++kk) {
;         const bf16x8 sf = *(const bf16x8*)(ST + (size_t)(es * 16 + li) * 128 + (kk * 4 + g) * 8);
; #pragma unroll
;         for (int ns = 0; ns < 2; ++ns) acc[es][ns] = __builtin_amdgcn_mfma_f32_16x16x32_bf16(sf, qf[ns][kk], acc[es][ns], 0, 0, 0);
;       }
	v_mfma_f32_16x16x32_bf16 v[40:43], v[180:183], v[84:87], 0
	v_mfma_f32_16x16x32_bf16 v[32:35], v[180:183], v[100:103], 0
	v_mfma_f32_16x16x32_bf16 v[40:43], v[184:187], v[88:91], v[40:43]
	v_mfma_f32_16x16x32_bf16 v[32:35], v[184:187], v[104:107], v[32:35]
	v_lshl_add_u64 v[44:45], v[48:49], 0, v[56:57]
	v_mfma_f32_16x16x32_bf16 v[40:43], v[188:191], v[92:95], v[40:43]
	v_mfma_f32_16x16x32_bf16 v[32:35], v[188:191], v[108:111], v[32:35]
	v_lshl_add_u64 v[44:45], v[48:49], 0, v[54:55]
	v_mfma_f32_16x16x32_bf16 v[40:43], v[192:195], v[96:99], v[40:43]
	v_mfma_f32_16x16x32_bf16 v[32:35], v[192:195], v[112:115], v[32:35]
	v_lshl_add_u64 v[44:45], v[62:63], 0, v[2:3]
	v_mfma_f32_16x16x32_bf16 v[48:51], v[196:199], v[84:87], 0
	v_mfma_f32_16x16x32_bf16 v[44:47], v[196:199], v[100:103], 0
	v_mfma_f32_16x16x32_bf16 v[48:51], v[200:203], v[88:91], v[48:51]
	v_mfma_f32_16x16x32_bf16 v[44:47], v[200:203], v[104:107], v[44:47]
	v_lshl_add_u64 v[58:59], v[62:63], 0, v[56:57]
	v_mfma_f32_16x16x32_bf16 v[48:51], v[204:207], v[92:95], v[48:51]
	v_mfma_f32_16x16x32_bf16 v[58:61], v[204:207], v[108:111], v[44:47]
	s_nop 2
	v_lshl_add_u64 v[44:45], v[62:63], 0, v[54:55]
	v_mfma_f32_16x16x32_bf16 v[44:47], v[220:223], v[96:99], v[48:51]
	s_nop 2
	v_lshl_add_u64 v[48:49], v[66:67], 0, v[2:3]
	v_mfma_f32_16x16x32_bf16 v[116:119], v[220:223], v[112:115], v[58:61]
	s_mov_b64 s[98:99], 0x6000
	v_lshl_add_u64 v[192:193], v[252:253], 0, s[98:99]
	global_load_dwordx4 v[180:183], v[192:193], off
	global_load_dwordx4 v[184:187], v[192:193], off offset:64
	global_load_dwordx4 v[188:191], v[192:193], off offset:128
	global_load_dwordx4 v[192:195], v[192:193], off offset:192
	s_mov_b64 s[98:99], 0x7000
	v_lshl_add_u64 v[220:221], v[252:253], 0, s[98:99]
	global_load_dwordx4 v[196:199], v[220:221], off
	global_load_dwordx4 v[200:203], v[220:221], off offset:64
	global_load_dwordx4 v[204:207], v[220:221], off offset:128
	global_load_dwordx4 v[220:223], v[220:221], off offset:192
	v_lshl_add_u64 v[62:63], v[66:67], 0, v[0:1]
	s_waitcnt vmcnt(8)
	v_mfma_f32_16x16x32_bf16 v[58:61], v[148:151], v[84:87], 0
	v_mfma_f32_16x16x32_bf16 v[48:51], v[148:151], v[100:103], 0
	v_mfma_f32_16x16x32_bf16 v[58:61], v[152:155], v[88:91], v[58:61]
	v_mfma_f32_16x16x32_bf16 v[48:51], v[152:155], v[104:107], v[48:51]
	v_lshl_add_u64 v[62:63], v[66:67], 0, v[56:57]
	v_mfma_f32_16x16x32_bf16 v[58:61], v[156:159], v[92:95], v[58:61]
	v_mfma_f32_16x16x32_bf16 v[62:65], v[156:159], v[108:111], v[48:51]
	s_nop 2
	v_lshl_add_u64 v[48:49], v[66:67], 0, v[54:55]
	v_mfma_f32_16x16x32_bf16 v[48:51], v[160:163], v[96:99], v[58:61]
	s_nop 2
	v_lshl_add_u64 v[58:59], v[70:71], 0, v[2:3]
	v_mfma_f32_16x16x32_bf16 v[120:123], v[160:163], v[112:115], v[62:65]
	v_lshl_add_u64 v[66:67], v[70:71], 0, v[0:1]
	v_mfma_f32_16x16x32_bf16 v[62:65], v[164:167], v[84:87], 0
	v_mfma_f32_16x16x32_bf16 v[58:61], v[164:167], v[100:103], 0
	v_mfma_f32_16x16x32_bf16 v[62:65], v[168:171], v[88:91], v[62:65]
	v_mfma_f32_16x16x32_bf16 v[58:61], v[168:171], v[104:107], v[58:61]
	v_lshl_add_u64 v[66:67], v[70:71], 0, v[56:57]
	v_mfma_f32_16x16x32_bf16 v[62:65], v[172:175], v[92:95], v[62:65]
	v_mfma_f32_16x16x32_bf16 v[58:61], v[172:175], v[108:111], v[58:61]
	v_lshl_add_u64 v[66:67], v[70:71], 0, v[54:55]
	v_lshl_add_u64 v[70:71], v[52:53], 0, s[10:11]
	v_mfma_f32_16x16x32_bf16 v[124:127], v[176:179], v[112:115], v[58:61]
	s_nop 2
	v_lshl_add_u64 v[58:59], v[70:71], 0, v[2:3]
	s_mov_b64 s[10:11], 0x2ba8b000
	v_mfma_f32_16x16x32_bf16 v[72:75], v[176:179], v[96:99], v[62:65]
	v_lshl_add_u64 v[66:67], v[70:71], 0, v[0:1]
	v_lshl_add_u64 v[52:53], v[52:53], 0, s[10:11]
	s_waitcnt vmcnt(0)
; __device__ void ret_out_item(const P& p, int bh, int c) {
;     ...
;   if (c > 0) {
; #pragma unroll
;     for (int es = 0; es < 8; ++es)
; #pragma unroll
;       for (int kk = 0; kk < 4; ++kk) {
;         const bf16x8 sf = *(const bf16x8*)(ST + (size_t)(es * 16 + li) * 128 + (kk * 4 + g) * 8);
; #pragma unroll
;         for (int ns = 0; ns < 2; ++ns) acc[es][ns] = __builtin_amdgcn_mfma_f32_16x16x32_bf16(sf, qf[ns][kk], acc[es][ns], 0, 0, 0);
;       }
; #pragma unroll
;     for (int ns = 0; ns < 2; ++ns) {
;       const float xi = exp2f((float)(32 * w + 16 * ns + li + 1) * lg);
; #pragma unroll
;       for (int es = 0; es < 8; ++es) {
;         acc[es][ns][0] *= xi; acc[es][ns][1] *= xi; acc[es][ns][2] *= xi; acc[es][ns][3] *= xi;
;       }
;     }
	v_mfma_f32_16x16x32_bf16 v[62:65], v[180:183], v[84:87], 0
	v_lshl_add_u64 v[2:3], v[52:53], 0, v[2:3]
	v_mfma_f32_16x16x32_bf16 v[58:61], v[180:183], v[100:103], 0
	v_mfma_f32_16x16x32_bf16 v[62:65], v[184:187], v[88:91], v[62:65]
	v_mfma_f32_16x16x32_bf16 v[58:61], v[184:187], v[104:107], v[58:61]
	v_lshl_add_u64 v[66:67], v[70:71], 0, v[56:57]
	v_mfma_f32_16x16x32_bf16 v[62:65], v[188:191], v[92:95], v[62:65]
	v_mfma_f32_16x16x32_bf16 v[58:61], v[188:191], v[108:111], v[58:61]
	v_lshl_add_u64 v[66:67], v[70:71], 0, v[54:55]
	v_mfma_f32_16x16x32_bf16 v[128:131], v[192:195], v[112:115], v[58:61]
	s_nop 3
	v_lshl_add_u64 v[2:3], v[52:53], 0, v[0:1]
	v_mfma_f32_16x16x32_bf16 v[76:79], v[192:195], v[96:99], v[62:65]
	v_lshl_add_u64 v[2:3], v[52:53], 0, v[56:57]
	v_mfma_f32_16x16x32_bf16 v[62:65], v[196:199], v[84:87], 0
	v_mfma_f32_16x16x32_bf16 v[58:61], v[196:199], v[100:103], 0
	v_mfma_f32_16x16x32_bf16 v[62:65], v[200:203], v[88:91], v[62:65]
	v_mfma_f32_16x16x32_bf16 v[58:61], v[200:203], v[104:107], v[58:61]
	v_lshl_add_u64 v[2:3], v[52:53], 0, v[54:55]
	v_add_u32_e32 v2, v143, v136
	v_add_u32_e32 v0, 1, v2
	v_cvt_f32_i32_e32 v0, v0
	v_mfma_f32_16x16x32_bf16 v[62:65], v[204:207], v[92:95], v[62:65]
	s_waitcnt lgkmcnt(0)
	v_mul_f32_e32 v3, s24, v0
	v_cmp_gt_f32_e32 vcc, s53, v3
	v_mfma_f32_16x16x32_bf16 v[56:59], v[204:207], v[108:111], v[58:61]
	s_nop 0
	v_cndmask_b32_e32 v3, 0, v242, vcc
	v_fmac_f32_e32 v3, s24, v0
	v_exp_f32_e32 v0, v3
	v_mfma_f32_16x16x32_bf16 v[80:83], v[220:223], v[96:99], v[62:65]
	v_cndmask_b32_e32 v3, 0, v241, vcc
	v_ldexp_f32 v0, v0, v3
	v_mfma_f32_16x16x32_bf16 v[132:135], v[220:223], v[112:115], v[56:59]
	v_mul_f32_e64 v62, v0, v30
	v_mul_f32_e64 v63, v0, v31
	v_pk_mul_f32 v[60:61], v[0:1], v[28:29] op_sel_hi:[0,1]
	v_pk_mul_f32 v[54:55], v[0:1], v[38:39] op_sel_hi:[0,1]
	v_pk_mul_f32 v[52:53], v[0:1], v[36:37] op_sel_hi:[0,1]
	v_pk_mul_f32 v[58:59], v[0:1], v[42:43] op_sel_hi:[0,1]
	v_pk_mul_f32 v[56:57], v[0:1], v[40:41] op_sel_hi:[0,1]
	v_pk_mul_f32 v[66:67], v[0:1], v[46:47] op_sel_hi:[0,1]
	v_pk_mul_f32 v[64:65], v[0:1], v[44:45] op_sel_hi:[0,1]
	v_pk_mul_f32 v[70:71], v[0:1], v[50:51] op_sel_hi:[0,1]
	v_pk_mul_f32 v[68:69], v[0:1], v[48:49] op_sel_hi:[0,1]
	v_pk_mul_f32 v[74:75], v[0:1], v[74:75] op_sel_hi:[0,1]
	v_pk_mul_f32 v[72:73], v[0:1], v[72:73] op_sel_hi:[0,1]
	v_pk_mul_f32 v[78:79], v[0:1], v[78:79] op_sel_hi:[0,1]
	v_pk_mul_f32 v[76:77], v[0:1], v[76:77] op_sel_hi:[0,1]
	v_pk_mul_f32 v[82:83], v[0:1], v[82:83] op_sel_hi:[0,1]
	v_pk_mul_f32 v[80:81], v[0:1], v[80:81] op_sel_hi:[0,1]
	v_add_u32_e32 v0, 17, v2
	v_cvt_f32_i32_e32 v0, v0
	v_mul_f32_e32 v2, s24, v0
	v_cmp_gt_f32_e32 vcc, s53, v2
	s_nop 1
	v_cndmask_b32_e32 v2, 0, v242, vcc
	v_fmac_f32_e32 v2, s24, v0
	v_exp_f32_e32 v0, v2
	v_cndmask_b32_e32 v2, 0, v241, vcc
	v_ldexp_f32 v0, v0, v2
	v_pk_mul_f32 v[50:51], v[0:1], v[22:23] op_sel_hi:[0,1]
	v_pk_mul_f32 v[48:49], v[0:1], v[20:21] op_sel_hi:[0,1]
	v_pk_mul_f32 v[46:47], v[0:1], v[26:27] op_sel_hi:[0,1]
	v_pk_mul_f32 v[44:45], v[0:1], v[24:25] op_sel_hi:[0,1]
	v_pk_mul_f32 v[42:43], v[0:1], v[34:35] op_sel_hi:[0,1]
	v_pk_mul_f32 v[40:41], v[0:1], v[32:33] op_sel_hi:[0,1]
	v_pk_mul_f32 v[38:39], v[0:1], v[118:119] op_sel_hi:[0,1]
	v_pk_mul_f32 v[36:37], v[0:1], v[116:117] op_sel_hi:[0,1]
	v_pk_mul_f32 v[34:35], v[0:1], v[122:123] op_sel_hi:[0,1]
	v_pk_mul_f32 v[32:33], v[0:1], v[120:121] op_sel_hi:[0,1]
	v_pk_mul_f32 v[30:31], v[0:1], v[126:127] op_sel_hi:[0,1]
	v_pk_mul_f32 v[28:29], v[0:1], v[124:125] op_sel_hi:[0,1]
	v_pk_mul_f32 v[26:27], v[0:1], v[130:131] op_sel_hi:[0,1]
	v_pk_mul_f32 v[24:25], v[0:1], v[128:129] op_sel_hi:[0,1]
	v_pk_mul_f32 v[22:23], v[0:1], v[134:135] op_sel_hi:[0,1]
	v_pk_mul_f32 v[20:21], v[0:1], v[132:133] op_sel_hi:[0,1]
	v_cmp_lt_i32_e32 vcc, -1, v145
	s_and_saveexec_b64 s[10:11], vcc
	s_cbranch_execz .LBB0_760
	s_branch .LBB0_764
